# fixup and x-init row loops: drop per-row store drain (vmcnt(0) at loop top moved to preheader)
# baseline (speedup 1.0000x reference)
.LBB0_19:
	s_and_b64 s[0:1], exec, s[40:41]
	s_or_b64 s[36:37], s[0:1], s[36:37]
	v_lshl_add_u64 v[36:37], v[36:37], 0, s[28:29]
	v_lshl_add_u64 v[38:39], v[38:39], 0, s[30:31]
	v_lshl_add_u64 v[40:41], v[40:41], 0, s[34:35]
	v_lshl_add_u64 v[42:43], v[42:43], 0, s[34:35]
	v_lshl_add_u64 v[44:45], v[44:45], 0, s[30:31]
	s_waitcnt vmcnt(8)
	v_mov_b64_e32 v[22:23], v[48:49]
	s_waitcnt vmcnt(7)
	v_mov_b64_e32 v[18:19], v[52:53]
	s_waitcnt vmcnt(6)
	v_mov_b64_e32 v[20:21], v[56:57]
	s_waitcnt vmcnt(5)
	v_mov_b64_e32 v[26:27], v[58:59]
	v_mov_b64_e32 v[28:29], v[46:47]
	v_mov_b64_e32 v[62:63], v[50:51]
	v_mov_b64_e32 v[24:25], v[54:55]
	v_mov_b64_e32 v[32:33], v[60:61]
	s_waitcnt vmcnt(4)
	v_mov_b32_e32 v30, v0
	s_andn2_b64 exec, exec, s[36:37]
	s_cbranch_execz .LBB0_67
.LBB0_20:
	v_add_u32_e32 v34, s26, v34
	v_cmp_gt_i32_e32 vcc, s78, v34
	v_cmp_lt_i32_e64 s[40:41], s85, v34
	v_mov_b32_e32 v0, v30
	s_and_saveexec_b64 s[0:1], vcc
	s_cbranch_execz .LBB0_22
	v_lshl_add_u64 v[46:47], s[10:11], 0, v[42:43]
	v_add_co_u32_e32 v48, vcc, 0x11040000, v46
	v_lshl_add_u64 v[64:65], s[10:11], 0, v[44:45]
	s_nop 0
	v_addc_co_u32_e32 v49, vcc, 0, v47, vcc
	v_add_co_u32_e32 v58, vcc, 0x9480000, v46
	s_nop 1
	v_addc_co_u32_e32 v59, vcc, 0, v47, vcc
	global_load_dwordx2 v[46:47], v[48:49], off
	global_load_dwordx2 v[50:51], v[48:49], off offset:512
	global_load_dwordx2 v[54:55], v[48:49], off offset:1024
	global_load_dwordx2 v[60:61], v[48:49], off offset:1536
	s_nop 0
	global_load_dwordx2 v[48:49], v[58:59], off
	global_load_dwordx2 v[52:53], v[58:59], off offset:512
	global_load_dwordx2 v[56:57], v[58:59], off offset:1024
	s_nop 0
	global_load_dwordx2 v[58:59], v[58:59], off offset:1536
	s_nop 0
	global_load_dword v0, v[64:65], off

.LBB0_29:
	s_and_b64 vcc, exec, s[2:3]
	s_cbranch_vccz .LBB0_105
	s_cmp_gt_i32 s18, 5
	s_mov_b64 s[0:1], -1
	s_cbranch_scc0 .LBB0_39
	v_ashrrev_i32_e32 v20, 6, v204
	s_lshl_b32 s0, s90, 3
	v_add_u32_e32 v18, s0, v20
	v_cmp_gt_i32_e32 vcc, s78, v18
	s_and_saveexec_b64 s[2:3], vcc
	s_cbranch_execz .LBB0_38
	v_and_b32_e32 v21, 63, v204
	v_readlane_b32 s8, v254, 46
	v_lshlrev_b32_e32 v0, 4, v21
	v_readlane_b32 s9, v254, 47
	v_ashrrev_i32_e32 v19, 31, v18
	v_lshlrev_b64 v[22:23], 11, v[18:19]
	s_waitcnt vmcnt(0)
	v_lshl_add_u64 v[2:3], s[8:9], 0, v[0:1]
	s_mov_b64 s[8:9], 0x3000
	v_lshl_add_u64 v[14:15], v[2:3], 0, s[8:9]
	v_add_co_u32_e32 v2, vcc, 0x3000, v2
	v_lshl_add_u64 v[24:25], s[20:21], 0, v[22:23]
	v_lshlrev_b32_e32 v0, 3, v21
	v_lshl_add_u64 v[22:23], s[12:13], 0, v[22:23]
	v_addc_co_u32_e32 v3, vcc, 0, v3, vcc
	v_lshl_add_u64 v[24:25], v[24:25], 0, v[0:1]
	v_lshl_add_u64 v[22:23], v[22:23], 0, v[0:1]
	global_load_dwordx4 v[2:5], v[2:3], off
	s_nop 0
	global_load_dwordx4 v[6:9], v[14:15], off offset:1024
	global_load_dwordx4 v[10:13], v[14:15], off offset:2048
	s_nop 0
	global_load_dwordx4 v[14:17], v[14:15], off offset:3072
	s_nop 0
	global_load_dwordx2 v[56:57], v[24:25], off
	global_load_dwordx2 v[50:51], v[22:23], off
	global_load_dwordx2 v[60:61], v[24:25], off offset:512
	global_load_dwordx2 v[46:47], v[22:23], off offset:512
	global_load_dwordx2 v[52:53], v[24:25], off offset:1024
	global_load_dwordx2 v[48:49], v[22:23], off offset:1024
	global_load_dwordx2 v[58:59], v[24:25], off offset:1536
	global_load_dwordx2 v[54:55], v[22:23], off offset:1536
	v_lshl_add_u64 v[22:23], v[18:19], 2, s[10:11]
	v_add_co_u32_e32 v22, vcc, s84, v22
	s_lshl_b32 s8, s92, 3
	s_nop 0
	v_addc_co_u32_e32 v23, vcc, 0, v23, vcc
	global_load_dword v28, v[22:23], off
	v_lshlrev_b32_e32 v19, 2, v21
	v_cmp_eq_u32_e64 s[38:39], 0, v21
	v_ashrrev_i32_e32 v21, 31, v20
	s_ashr_i32 s1, s0, 31
	v_lshl_add_u64 v[22:23], v[20:21], 0, s[0:1]
	v_add_u32_e32 v26, s8, v18
	v_lshl_add_u64 v[20:21], v[22:23], 2, v[146:147]
	v_lshlrev_b64 v[22:23], 11, v[22:23]
	v_ashrrev_i32_e32 v27, 31, v26
	s_ashr_i32 s9, s8, 31
	v_or_b32_e32 v22, v22, v0
	s_mov_b64 s[0:1], 0x9480400
	v_lshlrev_b64 v[24:25], 11, v[26:27]
	v_xor_b32_e32 v19, 0x80, v19
	s_lshl_b64 s[22:23], s[8:9], 2
	v_lshl_add_u64 v[22:23], v[22:23], 0, s[0:1]
	s_lshl_b64 s[28:29], s[8:9], 11
	v_or_b32_e32 v24, v24, v0
	v_lshl_add_u64 v[26:27], v[26:27], 2, v[146:147]
	s_mov_b64 s[30:31], 0
	s_waitcnt vmcnt(8)
	v_mov_b64_e32 v[30:31], v[56:57]
	s_waitcnt vmcnt(7)
	v_mov_b64_e32 v[32:33], v[50:51]
	s_waitcnt vmcnt(6)
	v_mov_b64_e32 v[34:35], v[60:61]
	s_waitcnt vmcnt(5)
	v_mov_b64_e32 v[36:37], v[46:47]
	s_waitcnt vmcnt(4)
	v_mov_b64_e32 v[38:39], v[52:53]
	s_waitcnt vmcnt(3)
	v_mov_b64_e32 v[40:41], v[48:49]
	s_waitcnt vmcnt(2)
	v_mov_b64_e32 v[44:45], v[58:59]
	s_waitcnt vmcnt(1)
	v_mov_b64_e32 v[42:43], v[54:55]
	s_waitcnt vmcnt(0)
	s_branch .LBB0_34

.LBB0_34:
	v_add_u32_e32 v18, s8, v18
	v_cmp_gt_i32_e32 vcc, s78, v18
	v_cmp_lt_i32_e64 s[40:41], s85, v18
	v_mov_b32_e32 v0, v28
	s_and_saveexec_b64 s[0:1], vcc
	s_cbranch_execz .LBB0_36
	v_lshl_add_u64 v[30:31], s[10:11], 0, v[24:25]
	v_add_co_u32_e32 v32, vcc, 0x11040000, v30
	v_lshl_add_u64 v[62:63], s[10:11], 0, v[26:27]
	s_nop 0
	v_addc_co_u32_e32 v33, vcc, 0, v31, vcc
	v_add_co_u32_e32 v42, vcc, 0x9480000, v30
	s_nop 1
	v_addc_co_u32_e32 v43, vcc, 0, v31, vcc
	global_load_dwordx2 v[30:31], v[32:33], off
	global_load_dwordx2 v[34:35], v[32:33], off offset:512
	global_load_dwordx2 v[38:39], v[32:33], off offset:1024
	global_load_dwordx2 v[44:45], v[32:33], off offset:1536
	s_nop 0
	global_load_dwordx2 v[32:33], v[42:43], off
	global_load_dwordx2 v[36:37], v[42:43], off offset:512
	global_load_dwordx2 v[40:41], v[42:43], off offset:1024
	s_nop 0
	global_load_dwordx2 v[42:43], v[42:43], off offset:1536
	s_nop 0
	global_load_dword v0, v[62:63], off

.LBB0_301:
	s_andn2_b64 vcc, exec, s[0:1]
	s_cbranch_vccnz .LBB0_310
	v_ashrrev_i32_e32 v20, 6, v204
	s_lshl_b32 s0, s90, 3
	v_add_u32_e32 v18, s0, v20
	v_cmp_gt_i32_e32 vcc, s78, v18
	s_and_saveexec_b64 s[2:3], vcc
	s_cbranch_execz .LBB0_309
	v_and_b32_e32 v21, 63, v204
	v_readlane_b32 s8, v254, 46
	v_lshlrev_b32_e32 v0, 4, v21
	v_readlane_b32 s9, v254, 47
	v_ashrrev_i32_e32 v19, 31, v18
	v_lshlrev_b64 v[22:23], 11, v[18:19]
	s_waitcnt vmcnt(0)
	v_lshl_add_u64 v[2:3], s[8:9], 0, v[0:1]
	s_mov_b64 s[8:9], 0x1000
	v_lshl_add_u64 v[14:15], v[2:3], 0, s[8:9]
	v_add_co_u32_e32 v2, vcc, 0x1000, v2
	v_lshl_add_u64 v[24:25], s[20:21], 0, v[22:23]
	v_lshlrev_b32_e32 v0, 3, v21
	v_lshl_add_u64 v[22:23], s[12:13], 0, v[22:23]
	v_addc_co_u32_e32 v3, vcc, 0, v3, vcc
	v_lshl_add_u64 v[24:25], v[24:25], 0, v[0:1]
	v_lshl_add_u64 v[22:23], v[22:23], 0, v[0:1]
	global_load_dwordx4 v[2:5], v[2:3], off
	s_nop 0
	global_load_dwordx4 v[6:9], v[14:15], off offset:1024
	global_load_dwordx4 v[10:13], v[14:15], off offset:2048
	s_nop 0
	global_load_dwordx4 v[14:17], v[14:15], off offset:3072
	s_nop 0
	global_load_dwordx2 v[56:57], v[24:25], off
	global_load_dwordx2 v[50:51], v[22:23], off
	global_load_dwordx2 v[60:61], v[24:25], off offset:512
	global_load_dwordx2 v[46:47], v[22:23], off offset:512
	global_load_dwordx2 v[52:53], v[24:25], off offset:1024
	global_load_dwordx2 v[48:49], v[22:23], off offset:1024
	global_load_dwordx2 v[58:59], v[24:25], off offset:1536
	global_load_dwordx2 v[54:55], v[22:23], off offset:1536
	v_lshl_add_u64 v[22:23], v[18:19], 2, s[10:11]
	v_add_co_u32_e32 v22, vcc, s84, v22
	s_lshl_b32 s8, s92, 3
	s_nop 0
	v_addc_co_u32_e32 v23, vcc, 0, v23, vcc
	global_load_dword v28, v[22:23], off
	v_lshlrev_b32_e32 v19, 2, v21
	v_cmp_eq_u32_e64 s[38:39], 0, v21
	v_ashrrev_i32_e32 v21, 31, v20
	s_ashr_i32 s1, s0, 31
	v_lshl_add_u64 v[22:23], v[20:21], 0, s[0:1]
	v_add_u32_e32 v26, s8, v18
	v_lshl_add_u64 v[20:21], v[22:23], 2, v[146:147]
	v_lshlrev_b64 v[22:23], 11, v[22:23]
	v_ashrrev_i32_e32 v27, 31, v26
	s_ashr_i32 s9, s8, 31
	v_or_b32_e32 v22, v22, v0
	s_mov_b64 s[0:1], 0x9480400
	v_lshlrev_b64 v[24:25], 11, v[26:27]
	v_xor_b32_e32 v19, 0x80, v19
	s_lshl_b64 s[22:23], s[8:9], 2
	v_lshl_add_u64 v[22:23], v[22:23], 0, s[0:1]
	s_lshl_b64 s[24:25], s[8:9], 11
	v_or_b32_e32 v24, v24, v0
	v_lshl_add_u64 v[26:27], v[26:27], 2, v[146:147]
	s_mov_b64 s[28:29], 0
	s_waitcnt vmcnt(8)
	v_mov_b64_e32 v[30:31], v[56:57]
	s_waitcnt vmcnt(7)
	v_mov_b64_e32 v[32:33], v[50:51]
	s_waitcnt vmcnt(6)
	v_mov_b64_e32 v[34:35], v[60:61]
	s_waitcnt vmcnt(5)
	v_mov_b64_e32 v[36:37], v[46:47]
	s_waitcnt vmcnt(4)
	v_mov_b64_e32 v[38:39], v[52:53]
	s_waitcnt vmcnt(3)
	v_mov_b64_e32 v[40:41], v[48:49]
	s_waitcnt vmcnt(2)
	v_mov_b64_e32 v[44:45], v[58:59]
	s_waitcnt vmcnt(1)
	v_mov_b64_e32 v[42:43], v[54:55]
	s_waitcnt vmcnt(0)
	s_branch .LBB0_305

.LBB0_637:
	s_ashr_i32 s0, s26, 6
	s_lshl_b32 s1, s90, 3
	s_add_i32 s2, s0, s1
	s_cmpk_gt_i32 s2, 0x41ff
	s_cbranch_scc1 .LBB0_644
	s_lshl_b32 s8, s92, 3
	s_add_i32 s0, s2, 0xffffc000
	s_ashr_i32 s3, s2, 31
	s_cmpk_lt_i32 s2, 0x4000
	s_cselect_b32 s9, 0, 8
	s_cselect_b32 s1, s3, 0
	s_cselect_b32 s0, s2, s0
	s_add_u32 s12, s80, s9
	s_addc_u32 s13, s81, 0
	s_load_dwordx2 s[12:13], s[12:13], 0x0
	s_lshl_b64 s[0:1], s[0:1], 12
	v_lshlrev_b32_e32 v0, 4, v34
	v_cmp_eq_u32_e64 s[38:39], 0, v34
	s_waitcnt lgkmcnt(0)
	s_add_u32 s0, s12, s0
	s_addc_u32 s1, s13, s1
	global_load_dwordx4 v[14:17], v0, s[0:1]
	global_load_dwordx4 v[10:13], v0, s[0:1] offset:1024
	global_load_dwordx4 v[6:9], v0, s[0:1] offset:2048
	global_load_dwordx4 v[2:5], v0, s[0:1] offset:3072
	s_lshl_b64 s[0:1], s[2:3], 2
	s_add_u32 s20, s0, 0x14182000
	s_addc_u32 s21, s1, 0
	s_ashr_i32 s9, s8, 31
	s_lshl_b64 s[0:1], s[2:3], 11
	v_xor_b32_e32 v0, 0x80, v35
	s_lshl_b64 s[12:13], s[8:9], 2
	v_lshl_or_b32 v36, v34, 3, s0
	v_mov_b32_e32 v37, s1
	s_lshl_b64 s[14:15], s[8:9], 11
	v_lshlrev_b32_e32 v34, 4, v34
	s_waitcnt vmcnt(0)
	s_branch .LBB0_640

.LBB0_640:
	s_add_i32 s2, s2, s8
	s_cmpk_gt_i32 s2, 0x41ff
	s_cselect_b64 s[16:17], -1, 0
	s_cmpk_lt_i32 s2, 0x4200
	v_mov_b32_e32 v18, v14
	v_mov_b32_e32 v19, v15
	v_mov_b32_e32 v20, v16
	v_mov_b32_e32 v21, v17
	v_mov_b32_e32 v22, v10
	v_mov_b32_e32 v23, v11
	v_mov_b32_e32 v24, v12
	v_mov_b32_e32 v25, v13
	v_mov_b32_e32 v26, v6
	v_mov_b32_e32 v27, v7
	v_mov_b32_e32 v28, v8
	v_mov_b32_e32 v29, v9
	v_mov_b32_e32 v30, v2
	v_mov_b32_e32 v31, v3
	v_mov_b32_e32 v32, v4
	v_mov_b32_e32 v33, v5
	s_cbranch_scc0 .LBB0_642
	s_add_i32 s0, s2, 0xffffc000
	s_ashr_i32 s1, s2, 31
	s_cmpk_lt_i32 s2, 0x4000
	s_cselect_b32 s3, 0, 8
	s_cselect_b32 s1, s1, 0
	s_cselect_b32 s0, s2, s0
	s_add_u32 s18, s80, s3
	s_addc_u32 s19, s81, 0
	s_load_dwordx2 s[18:19], s[18:19], 0x0
	s_lshl_b64 s[0:1], s[0:1], 12
	s_waitcnt lgkmcnt(0)
	s_add_u32 s0, s18, s0
	s_addc_u32 s1, s19, s1
	global_load_dwordx4 v[18:21], v34, s[0:1]
	global_load_dwordx4 v[22:25], v34, s[0:1] offset:1024
	global_load_dwordx4 v[26:29], v34, s[0:1] offset:2048
	global_load_dwordx4 v[30:33], v34, s[0:1] offset:3072
